# code placement: recurrence loop (and everything after it) shifted by 4 bytes with one s_nop
# speedup vs baseline: 1.0371x; 1.0057x over previous
.LBB0_2880:
	v_readlane_b32 s2, v255, 20
	v_lshrrev_b32_e32 v8, 2, v46
	v_and_b32_e32 v0, 8, v158
	v_lshl_add_u32 v7, v46, 2, s2
	s_movk_i32 s2, 0x540
	v_and_b32_e32 v6, 3, v158
	v_mul_lo_u32 v47, v8, s2
	v_lshlrev_b32_e32 v8, 4, v158
	v_cmp_eq_u32_e32 vcc, 0, v0
	v_and_b32_e32 v0, 4, v158
	v_cmp_eq_u32_e64 s[6:7], 0, v6
	v_cmp_eq_u32_e64 s[8:9], 1, v6
	v_cmp_eq_u32_e64 s[10:11], 2, v6
	v_cmp_eq_u32_e64 s[12:13], 3, v6
	v_lshlrev_b32_e32 v6, 8, v6
	v_and_b32_e32 v8, 0xc0, v8
	v_cmp_eq_u32_e64 s[4:5], 0, v0
	v_lshlrev_b32_e32 v0, 4, v159
	v_and_b32_e32 v48, 48, v158
	v_add3_u32 v49, v7, v6, v8
	s_nop 0
